# helpers poll the published flag five times more often (faster reaction at the phase ends)
# speedup vs baseline: 1.0018x; 1.0011x over previous
.Lhu_poll:
	global_load_dword v2, v1, s[74:75] offset:260 sc1
	s_waitcnt vmcnt(0)
	v_readfirstlane_b32 s0, v2
	s_nop 3
	s_cmp_lg_u32 s0, 0
	s_cbranch_scc1 .Lhu_got
	s_sleep 8
	s_add_u32 s77, s77, 1
	s_cmp_lt_u32 s77, 2000
	s_cbranch_scc1 .Lhu_poll

.Lha_poll:
	global_load_dword v2, v1, s[22:23] offset:388 sc1
	s_waitcnt vmcnt(0)
	v_readfirstlane_b32 s21, v2
	s_nop 3
	s_cmp_lg_u32 s21, 0
	s_cbranch_scc1 .Lha_got
	s_sleep 8
	s_add_u32 s25, s25, 1
	s_cmp_lt_u32 s25, 2000
	s_cbranch_scc1 .Lha_poll
